# speedup vs baseline: 1.0062x; 1.0062x over previous
; #define LAS __attribute__((address_space(3)))
; __device__ __forceinline__ void p0_transpose_item(const float* W, int K, int N, const float* gain, const float* gain2  , bf16_t* WT, LAS unsigned* scr, int item, int lane) {
;     const int nblk = N / 64, kb = item / nblk, nb = item % nblk, k0 = 64 * kb, n0 = 64 * nb;
;     if (gain2 && k0 >= 1024) gain = gain2 - 1024;
;     const int n4 = lane & 15, kq = lane >> 4;
;     f32x4 r0[8], r1[8];
;     const float* src = W + (size_t)(k0 + 2 * kq) * N + n0 + 4 * n4;
; #pragma unroll
;     for (int j = 0; j < 8; ++j) { r0[j] = __builtin_nontemporal_load((const f32x4*)(src + (size_t)(8 * j) * N)); r1[j] = __builtin_nontemporal_load((const f32x4*)(src + (size_t)(8 * j + 1) * N)); }
; __device__ __forceinline__ void p0_prologue(const Params& p, LAS unsigned char* lds, int tid) {
;     ...
;     for (int it = gw; it < I_LAYER * DEPTH; it += NGW) {
;         const int l = it / I_LAYER; int r = it % I_LAYER;
;         unsigned char* wl = p.ws + (size_t)l * LAYER_BYTES;
;         if (r < I_IN) { p0_transpose_item(p.in[3] + (size_t)l * DM * INW, DM, INW, p.in[2] + l * DM, nullptr, (bf16_t*)(wl + LO_WIN), scr, r, lane); continue; } r -= I_IN;
.Lmy_p0_cont:
	v_add_u32_e32 v66, s10, v66
	v_cmp_lt_i32_e32 vcc, s73, v66
	v_add_u32_e32 v110, s11, v110
	s_or_b64 s[14:15], vcc, s[14:15]
	v_add_u32_e32 v111, s36, v111
	s_andn2_b64 exec, exec, s[14:15]
	s_cbranch_execz .LBB0_181
.LBB0_118:
	s_mov_b32 s0, 0x30c30c31
	v_mul_hi_i32 v2, v66, s0
	v_lshrrev_b32_e32 v3, 31, v2
	v_ashrrev_i32_e32 v2, 11, v2
	v_add_u32_e32 v76, v2, v3
	s_mov_b32 s0, 0x6400000
	v_mul_i32_i24_e32 v3, 0x2a00, v76
	v_mad_i64_i32 v[74:75], s[0:1], v76, s0, v[72:73]
	v_sub_u32_e32 v2, v66, v3
	v_cmp_lt_i32_e32 vcc, 0, v76
	s_movk_i32 s0, 0x1c00
	v_cmp_gt_i32_e64 s[28:29], s0, v2
	s_nop 1
	s_and_b64 vcc, vcc, s[28:29]
	s_cbranch_vccnz .Lmy_p0_cont
	s_movk_i32 s0, 0x4ff
	v_ashrrev_i32_e32 v77, 31, v76
	v_cmp_lt_i32_e32 vcc, s0, v2
	s_and_saveexec_b64 s[0:1], vcc
	s_xor_b64 s[26:27], exec, s[0:1]
	s_cbranch_execz .LBB0_164
	s_movk_i32 s0, 0x14ff
	v_cmp_lt_u32_e32 vcc, s0, v2
	s_and_saveexec_b64 s[0:1], vcc
	s_xor_b64 s[0:1], exec, s[0:1]
	s_cbranch_execz .LBB0_145
	s_movk_i32 s28, 0x24ff
	v_cmp_lt_u32_e32 vcc, s28, v2
	s_and_saveexec_b64 s[28:29], vcc
	s_xor_b64 s[28:29], exec, s[28:29]
	s_cbranch_execz .LBB0_142
	s_movk_i32 s30, 0x25ff
	v_cmp_lt_u32_e32 vcc, s30, v2
	s_and_saveexec_b64 s[30:31], vcc
	s_xor_b64 s[30:31], exec, s[30:31]
	s_cbranch_execz .LBB0_139
	v_add_u16_e32 v80, 0xda00, v2
	v_lshrrev_b16_e32 v2, 5, v80
	v_readlane_b32 s40, v253, 18
	v_lshlrev_b32_e32 v85, 6, v2
	v_lshlrev_b32_e32 v2, 6, v3
	v_lshlrev_b64 v[4:5], 24, v[76:77]
	v_readlane_b32 s46, v253, 24
	v_readlane_b32 s47, v253, 25
	v_sub_u32_e32 v2, v110, v2
	v_or_b32_e32 v81, v85, v67
	v_lshl_add_u64 v[4:5], s[46:47], 0, v[4:5]
	v_and_b32_e32 v84, 0x7c0, v2
	v_lshlrev_b32_e32 v2, 13, v81
	v_mov_b32_e32 v3, v69
	v_lshl_add_u64 v[2:3], v[4:5], 0, v[2:3]
	v_lshlrev_b32_e32 v4, 2, v84
	v_mov_b32_e32 v5, v69
	v_lshl_add_u64 v[2:3], v[2:3], 0, v[4:5]
	v_lshl_add_u64 v[2:3], v[2:3], 0, v[68:69]
	v_add_co_u32_e32 v4, vcc, s37, v2
	v_lshlrev_b32_e32 v76, 10, v76
	s_nop 0
	v_addc_co_u32_e32 v5, vcc, 0, v3, vcc
	global_load_dwordx4 v[58:61], v[2:3], off nt
	global_load_dwordx4 v[62:65], v[4:5], off nt
	v_add_co_u32_e32 v4, vcc, s38, v2
	v_ashrrev_i32_e32 v77, 31, v76
	s_nop 0
	v_addc_co_u32_e32 v5, vcc, 0, v3, vcc
	v_add_co_u32_e32 v6, vcc, s39, v2
	v_readlane_b32 s42, v253, 20
	s_nop 0
	v_addc_co_u32_e32 v7, vcc, 0, v3, vcc
	global_load_dwordx4 v[50:53], v[4:5], off nt
	global_load_dwordx4 v[54:57], v[6:7], off nt
	v_add_co_u32_e32 v4, vcc, s2, v2
	v_readlane_b32 s43, v253, 21
	s_nop 0
	v_addc_co_u32_e32 v5, vcc, 0, v3, vcc
	v_add_co_u32_e32 v6, vcc, s3, v2
	v_readlane_b32 s44, v253, 22
	s_nop 0
	v_addc_co_u32_e32 v7, vcc, 0, v3, vcc
	global_load_dwordx4 v[42:45], v[4:5], off nt
	global_load_dwordx4 v[46:49], v[6:7], off nt
	v_add_co_u32_e32 v4, vcc, s76, v2
	v_readlane_b32 s45, v253, 23
	s_nop 0
	v_addc_co_u32_e32 v5, vcc, 0, v3, vcc
	v_add_co_u32_e32 v6, vcc, s77, v2
	v_lshlrev_b64 v[76:77], 2, v[76:77]
	s_nop 0
	v_addc_co_u32_e32 v7, vcc, 0, v3, vcc
	global_load_dwordx4 v[34:37], v[4:5], off nt
	global_load_dwordx4 v[38:41], v[6:7], off nt
	v_add_co_u32_e32 v4, vcc, s78, v2
	s_movk_i32 s34, 0x1ff
	s_nop 0
	v_addc_co_u32_e32 v5, vcc, 0, v3, vcc
	v_add_co_u32_e32 v6, vcc, s79, v2
	v_lshl_add_u64 v[78:79], s[42:43], 0, v[76:77]
	s_nop 0
	v_addc_co_u32_e32 v7, vcc, 0, v3, vcc
	global_load_dwordx4 v[26:29], v[4:5], off nt
	s_waitcnt lgkmcnt(0)
	global_load_dwordx4 v[30:33], v[6:7], off nt
	v_add_co_u32_e32 v4, vcc, s80, v2
	v_lshl_add_u64 v[76:77], s[44:45], 0, v[76:77]
	s_nop 0
	v_addc_co_u32_e32 v5, vcc, 0, v3, vcc
	v_add_co_u32_e32 v6, vcc, s81, v2
	v_lshl_add_u64 v[76:77], v[76:77], 0, s[16:17]
	s_nop 0
	v_addc_co_u32_e32 v7, vcc, 0, v3, vcc
	global_load_dwordx4 v[18:21], v[4:5], off nt
	global_load_dwordx4 v[22:25], v[6:7], off nt
	v_add_co_u32_e32 v4, vcc, s82, v2
	v_mov_b32_e32 v82, 1.0
	s_nop 0
	v_addc_co_u32_e32 v5, vcc, 0, v3, vcc
	v_add_co_u32_e32 v6, vcc, s83, v2
	v_mov_b32_e32 v83, 1.0
	s_nop 0
	v_addc_co_u32_e32 v7, vcc, 0, v3, vcc
	global_load_dwordx4 v[10:13], v[4:5], off nt
	global_load_dwordx4 v[14:17], v[6:7], off nt
	v_add_co_u32_e32 v4, vcc, s84, v2
	v_readlane_b32 s41, v253, 19
	s_nop 0
	v_addc_co_u32_e32 v5, vcc, 0, v3, vcc
	v_add_co_u32_e32 v6, vcc, 0x72000, v2
	v_readlane_b32 s48, v253, 26
	s_nop 0
	v_addc_co_u32_e32 v7, vcc, 0, v3, vcc
	global_load_dwordx4 v[2:5], v[4:5], off nt
	s_nop 0
	global_load_dwordx4 v[6:9], v[6:7], off nt
	v_cmp_lt_u16_e32 vcc, s34, v80
	s_and_b64 vcc, s[6:7], vcc
	v_mov_b32_e32 v80, 1.0
	v_cndmask_b32_e32 v77, v79, v77, vcc
	v_cndmask_b32_e32 v76, v78, v76, vcc
	v_cmp_ne_u64_e32 vcc, 0, v[76:77]
	v_lshlrev_b32_e32 v78, 2, v81
	v_readlane_b32 s49, v253, 27
	v_readlane_b32 s50, v253, 28
	v_readlane_b32 s51, v253, 29
	v_readlane_b32 s52, v253, 30
	v_readlane_b32 s53, v253, 31
	v_readlane_b32 s54, v253, 32
	v_readlane_b32 s55, v253, 33
	s_and_saveexec_b64 s[34:35], vcc
	s_cbranch_execz .LBB0_124
	v_mov_b32_e32 v79, v69
	v_lshl_add_u64 v[82:83], v[76:77], 0, v[78:79]
	global_load_dwordx2 v[82:83], v[82:83], off

; #define LAS __attribute__((address_space(3)))
; __device__ __forceinline__ void p0_prologue(const Params& p, LAS unsigned char* lds, int tid) {
;     ...
;     LAS unsigned* scr = (LAS unsigned*)(lds + wave * 8192);
;     const int gw = blockIdx.x * 8 + wave, NGW = gridDim.x * 8;
;     ...
;     for (int it = gw; it < I_LAYER * DEPTH; it += NGW) {
;         const int l = it / I_LAYER; int r = it % I_LAYER;
;         unsigned char* wl = p.ws + (size_t)l * LAYER_BYTES;
.LBB0_427:
	v_readlane_b32 s98, v254, 36
	v_readlane_b32 s99, v253, 34
	s_cmp_gt_u32 s98, 2
	s_cbranch_scc1 .Lmy_w_skip
	s_cmp_lt_u32 s99, 64
	s_cbranch_scc1 .Lmy_w_skip
	v_writelane_b32 v140, s0, 0
	v_writelane_b32 v140, s1, 1
	v_writelane_b32 v140, s2, 2
	v_writelane_b32 v140, s3, 3
	v_writelane_b32 v140, s4, 4
	v_writelane_b32 v140, s5, 5
	v_writelane_b32 v140, s6, 6
	v_writelane_b32 v140, s7, 7
	v_writelane_b32 v140, s8, 8
	v_writelane_b32 v140, s9, 9
	v_writelane_b32 v140, s10, 10
	v_writelane_b32 v140, s11, 11
	v_writelane_b32 v140, s12, 12
	v_writelane_b32 v140, s13, 13
	v_writelane_b32 v140, s14, 14
	v_writelane_b32 v140, s15, 15
	v_writelane_b32 v140, s16, 16
	v_writelane_b32 v140, s17, 17
	v_writelane_b32 v140, s18, 18
	v_writelane_b32 v140, s19, 19
	v_writelane_b32 v140, s20, 20
	v_writelane_b32 v140, s21, 21
	v_writelane_b32 v140, s22, 22
	v_writelane_b32 v140, s23, 23
	v_writelane_b32 v140, s24, 24
	v_writelane_b32 v140, s25, 25
	v_writelane_b32 v140, s26, 26
	v_writelane_b32 v140, s27, 27
	v_writelane_b32 v140, s28, 28
	v_writelane_b32 v140, s29, 29
	v_writelane_b32 v140, s30, 30
	v_writelane_b32 v140, s31, 31
	v_writelane_b32 v140, s32, 32
	v_writelane_b32 v140, s33, 33
	v_writelane_b32 v140, s34, 34
	v_writelane_b32 v140, s35, 35
	v_writelane_b32 v140, s36, 36
	v_writelane_b32 v140, s37, 37
	v_writelane_b32 v140, s38, 38
	v_writelane_b32 v140, s39, 39
	v_writelane_b32 v140, s40, 40
	v_writelane_b32 v140, s41, 41
	v_writelane_b32 v140, s42, 42
	v_writelane_b32 v140, s43, 43
	v_writelane_b32 v140, s44, 44
	v_writelane_b32 v140, s45, 45
	v_writelane_b32 v140, s46, 46
	v_writelane_b32 v140, s47, 47
	v_writelane_b32 v140, s48, 48
	v_writelane_b32 v140, s49, 49
	v_writelane_b32 v140, s50, 50
	v_writelane_b32 v140, s51, 51
	v_writelane_b32 v140, s52, 52
	v_writelane_b32 v140, s53, 53
	v_writelane_b32 v140, s54, 54
	v_writelane_b32 v140, s55, 55
	v_writelane_b32 v140, s56, 56
	v_writelane_b32 v140, s57, 57
	v_writelane_b32 v140, s58, 58
	v_writelane_b32 v140, s59, 59
	v_writelane_b32 v140, s60, 60
	v_writelane_b32 v140, s61, 61
	v_writelane_b32 v140, s62, 62
	v_writelane_b32 v140, s63, 63
	v_writelane_b32 v141, s64, 0
	v_writelane_b32 v141, s65, 1
	v_writelane_b32 v141, s66, 2
	v_writelane_b32 v141, s67, 3
	v_writelane_b32 v141, s68, 4
	v_writelane_b32 v141, s69, 5
	v_writelane_b32 v141, s70, 6
	v_writelane_b32 v141, s71, 7
	v_writelane_b32 v141, s72, 8
	v_writelane_b32 v141, s73, 9
	v_writelane_b32 v141, s74, 10
	v_writelane_b32 v141, s75, 11
	v_writelane_b32 v141, s76, 12
	v_writelane_b32 v141, s77, 13
	v_writelane_b32 v141, s78, 14
	v_writelane_b32 v141, s79, 15
	v_writelane_b32 v141, s80, 16
	v_writelane_b32 v141, s81, 17
	v_writelane_b32 v141, s82, 18
	v_writelane_b32 v141, s83, 19
	v_writelane_b32 v141, s84, 20
	v_writelane_b32 v141, s85, 21
	v_writelane_b32 v141, s86, 22
	v_writelane_b32 v141, s87, 23
	v_writelane_b32 v141, s88, 24
	v_writelane_b32 v141, s89, 25
	v_writelane_b32 v141, s90, 26
	v_writelane_b32 v141, s91, 27
	v_writelane_b32 v141, s92, 28
	v_writelane_b32 v141, s93, 29
	v_writelane_b32 v141, s94, 30
	v_writelane_b32 v141, s95, 31
	v_writelane_b32 v141, s96, 32
	v_writelane_b32 v141, s97, 33
	s_add_i32 s98, s98, 1
	s_mul_i32 s98, s98, 0x2a00
	s_mov_b32 s0, s98
	s_add_i32 s98, s98, 0x1c00
	s_sub_i32 s1, s99, 64
	s_lshl_b32 s1, s1, 3
	s_add_i32 s0, s0, s1
	v_and_b32_e32 v34, 63, v201
	v_lshrrev_b32_e32 v35, 6, v201
	v_lshlrev_b32_e32 v36, 3, v201
	v_add_u32_e32 v90, s0, v35
	s_add_i32 s99, s98, -1
	s_movk_i32 s10, 0x600
	v_readlane_b32 s62, v255, 8
	v_readlane_b32 s63, v255, 9
	s_branch .Lmy_w_entry
